# P1 epilogue: k-section (act 4) chunk path also specialised, joins the generic k-max tail
# baseline (speedup 1.0000x reference)
.Lmy_e1_act4:
	s_xor_b64 s[74:75], s[74:75], -1
	s_xor_b64 s[76:77], s[76:77], -1
	s_andn2_b64 vcc, exec, s[54:55]
	v_pk_mul_f32 v[146:147], v[128:129], v[128:129]
	v_pk_mul_f32 v[148:149], v[126:127], v[126:127]
	s_nop 0
	v_pk_mov_b32 v[150:151], v[148:149], v[146:147] op_sel:[1,0]
	v_mov_b32_e32 v149, v147
	v_pk_add_f32 v[146:147], v[150:151], v[148:149]
	v_pk_mul_f32 v[148:149], v[124:125], v[124:125]
	v_pk_mul_f32 v[150:151], v[122:123], v[122:123]
	v_mov_b32_e32 v152, v148
	v_mov_b32_e32 v153, v150
	v_mov_b32_e32 v150, v149
	v_pk_add_f32 v[148:149], v[152:153], v[150:151]
	v_add_f32_e32 v146, v146, v147
	v_add_f32_e32 v146, v146, v149
	v_add_f32_e32 v146, v148, v146
	v_and_b32_e32 v148, 64, v160
	v_xor_b32_e32 v147, 16, v160
	v_add_u32_e32 v148, 64, v148
	v_cmp_lt_i32_e32 vcc, v147, v148
	s_nop 1
	v_cndmask_b32_e32 v147, v160, v147, vcc
	v_lshlrev_b32_e32 v147, 2, v147
	ds_bpermute_b32 v147, v147, v146
	s_waitcnt lgkmcnt(0)
	v_add_f32_e32 v146, v146, v147
	v_xor_b32_e32 v147, 32, v160
	v_cmp_lt_i32_e32 vcc, v147, v148
	s_nop 1
	v_cndmask_b32_e32 v147, v160, v147, vcc
	v_lshlrev_b32_e32 v147, 2, v147
	ds_bpermute_b32 v147, v147, v146
	s_waitcnt lgkmcnt(0)
	v_add_f32_e32 v146, v146, v147
	v_max_f32_e32 v162, 0, v146
	v_mov_b32_e32 v149, v129
	v_mov_b32_e32 v148, v128
	v_mov_b32_e32 v147, v127
	v_mov_b32_e32 v146, v126
	v_mov_b32_e32 v153, v125
	v_mov_b32_e32 v152, v124
	v_mov_b32_e32 v151, v123
	v_mov_b32_e32 v150, v122
	s_mov_b64 s[78:79], 0
	s_lshl_b32 s6, s6, 8
	s_add_i32 s6, s7, s6
	v_or_b32_e32 v122, s6, v156
	s_lshl_b32 s6, s72, 1
	s_add_u32 s6, s38, s6
	v_lshl_add_u32 v161, s8, 8, v154
	s_addc_u32 s7, s39, 0
	v_ashrrev_i32_e32 v123, 31, v122
	v_lshl_add_u64 v[122:123], v[122:123], 1, s[6:7]
	v_mad_i64_i32 v[124:125], s[6:7], s70, v161, 0
	v_lshl_add_u64 v[124:125], v[124:125], 1, v[122:123]
	v_cvt_pk_bf16_f32 v126, v146, v147
	v_cvt_pk_bf16_f32 v127, v148, v149
	v_cvt_pk_bf16_f32 v128, v150, v151
	v_cvt_pk_bf16_f32 v129, v152, v153
	global_store_dwordx4 v[124:125], v[126:129], off
	s_andn2_b64 vcc, exec, s[54:55]
	s_nop 0
	v_pk_mul_f32 v[126:127], v[120:121], v[120:121]
	v_pk_mul_f32 v[128:129], v[118:119], v[118:119]
	s_nop 0
	v_pk_mov_b32 v[146:147], v[128:129], v[126:127] op_sel:[1,0]
	v_mov_b32_e32 v129, v127
	v_pk_add_f32 v[126:127], v[146:147], v[128:129]
	v_pk_mul_f32 v[128:129], v[116:117], v[116:117]
	v_pk_mul_f32 v[146:147], v[114:115], v[114:115]
	v_mov_b32_e32 v148, v128
	v_mov_b32_e32 v149, v146
	v_mov_b32_e32 v146, v129
	v_pk_add_f32 v[128:129], v[148:149], v[146:147]
	v_add_f32_e32 v126, v126, v127
	v_add_f32_e32 v126, v126, v129
	v_add_f32_e32 v126, v128, v126
	v_and_b32_e32 v128, 64, v160
	v_xor_b32_e32 v127, 16, v160
	v_add_u32_e32 v128, 64, v128
	v_cmp_lt_i32_e32 vcc, v127, v128
	s_nop 1
	v_cndmask_b32_e32 v127, v160, v127, vcc
	v_lshlrev_b32_e32 v127, 2, v127
	ds_bpermute_b32 v127, v127, v126
	s_waitcnt lgkmcnt(0)
	v_add_f32_e32 v126, v126, v127
	v_xor_b32_e32 v127, 32, v160
	v_cmp_lt_i32_e32 vcc, v127, v128
	s_nop 1
	v_cndmask_b32_e32 v127, v160, v127, vcc
	v_lshlrev_b32_e32 v127, 2, v127
	ds_bpermute_b32 v127, v127, v126
	s_waitcnt lgkmcnt(0)
	v_add_f32_e32 v126, v126, v127
	v_max_f32_e32 v127, v162, v162
	v_max_f32_e32 v150, v127, v126
	v_mov_b32_e32 v129, v121
	v_mov_b32_e32 v128, v120
	v_mov_b32_e32 v127, v119
	v_mov_b32_e32 v126, v118
	v_mov_b32_e32 v149, v117
	v_mov_b32_e32 v148, v116
	v_mov_b32_e32 v147, v115
	v_mov_b32_e32 v146, v114
	v_cvt_pk_bf16_f32 v114, v126, v127
	v_cvt_pk_bf16_f32 v115, v128, v129
	v_cvt_pk_bf16_f32 v116, v146, v147
	v_cvt_pk_bf16_f32 v117, v148, v149
	global_store_dwordx4 v[124:125], v[114:117], off offset:256
	s_andn2_b64 vcc, exec, s[54:55]
	s_nop 0
	v_pk_mul_f32 v[114:115], v[112:113], v[112:113]
	v_pk_mul_f32 v[116:117], v[110:111], v[110:111]
	s_nop 0
	v_pk_mov_b32 v[118:119], v[116:117], v[114:115] op_sel:[1,0]
	v_mov_b32_e32 v117, v115
	v_pk_add_f32 v[114:115], v[118:119], v[116:117]
	v_pk_mul_f32 v[116:117], v[108:109], v[108:109]
	v_pk_mul_f32 v[118:119], v[106:107], v[106:107]
	v_mov_b32_e32 v120, v116
	v_mov_b32_e32 v121, v118
	v_mov_b32_e32 v118, v117
	v_pk_add_f32 v[116:117], v[120:121], v[118:119]
	v_add_f32_e32 v114, v114, v115
	v_add_f32_e32 v114, v114, v117
	v_add_f32_e32 v114, v116, v114
	v_and_b32_e32 v116, 64, v160
	v_xor_b32_e32 v115, 16, v160
	v_add_u32_e32 v116, 64, v116
	v_cmp_lt_i32_e32 vcc, v115, v116
	s_nop 1
	v_cndmask_b32_e32 v115, v160, v115, vcc
	v_lshlrev_b32_e32 v115, 2, v115
	ds_bpermute_b32 v115, v115, v114
	s_waitcnt lgkmcnt(0)
	v_add_f32_e32 v114, v114, v115
	v_xor_b32_e32 v115, 32, v160
	v_cmp_lt_i32_e32 vcc, v115, v116
	s_nop 1
	v_cndmask_b32_e32 v115, v160, v115, vcc
	v_lshlrev_b32_e32 v115, 2, v115
	ds_bpermute_b32 v115, v115, v114
	s_waitcnt lgkmcnt(0)
	v_add_f32_e32 v114, v114, v115
	v_max_f32_e32 v115, v150, v150
	v_max_f32_e32 v124, v115, v114
	v_mov_b32_e32 v117, v113
	v_mov_b32_e32 v116, v112
	v_mov_b32_e32 v115, v111
	v_mov_b32_e32 v114, v110
	v_mov_b32_e32 v121, v109
	v_mov_b32_e32 v120, v108
	v_mov_b32_e32 v119, v107
	v_mov_b32_e32 v118, v106
	v_or_b32_e32 v106, 16, v161
	v_mad_i64_i32 v[106:107], s[72:73], s70, v106, 0
	v_lshl_add_u64 v[106:107], v[106:107], 1, v[122:123]
	v_cvt_pk_bf16_f32 v108, v114, v115
	v_cvt_pk_bf16_f32 v109, v116, v117
	v_cvt_pk_bf16_f32 v110, v118, v119
	v_cvt_pk_bf16_f32 v111, v120, v121
	global_store_dwordx4 v[106:107], v[108:111], off
	s_andn2_b64 vcc, exec, s[54:55]
	s_nop 0
	v_pk_mul_f32 v[108:109], v[104:105], v[104:105]
	v_pk_mul_f32 v[110:111], v[102:103], v[102:103]
	s_nop 0
	v_pk_mov_b32 v[112:113], v[110:111], v[108:109] op_sel:[1,0]
	v_mov_b32_e32 v111, v109
	v_pk_add_f32 v[108:109], v[112:113], v[110:111]
	v_pk_mul_f32 v[110:111], v[100:101], v[100:101]
	v_pk_mul_f32 v[112:113], v[98:99], v[98:99]
	v_mov_b32_e32 v114, v110
	v_mov_b32_e32 v115, v112
	v_mov_b32_e32 v112, v111
	v_pk_add_f32 v[110:111], v[114:115], v[112:113]
	v_add_f32_e32 v108, v108, v109
	v_add_f32_e32 v108, v108, v111
	v_add_f32_e32 v108, v110, v108
	v_and_b32_e32 v110, 64, v160
	v_xor_b32_e32 v109, 16, v160
	v_add_u32_e32 v110, 64, v110
	v_cmp_lt_i32_e32 vcc, v109, v110
	s_nop 1
	v_cndmask_b32_e32 v109, v160, v109, vcc
	v_lshlrev_b32_e32 v109, 2, v109
	ds_bpermute_b32 v109, v109, v108
	s_waitcnt lgkmcnt(0)
	v_add_f32_e32 v108, v108, v109
	v_xor_b32_e32 v109, 32, v160
	v_cmp_lt_i32_e32 vcc, v109, v110
	s_nop 1
	v_cndmask_b32_e32 v109, v160, v109, vcc
	v_lshlrev_b32_e32 v109, 2, v109
	ds_bpermute_b32 v109, v109, v108
	s_waitcnt lgkmcnt(0)
	v_add_f32_e32 v108, v108, v109
	v_max_f32_e32 v109, v124, v124
	v_max_f32_e32 v116, v109, v108
	v_mov_b32_e32 v111, v105
	v_mov_b32_e32 v110, v104
	v_mov_b32_e32 v109, v103
	v_mov_b32_e32 v108, v102
	v_mov_b32_e32 v115, v101
	v_mov_b32_e32 v114, v100
	v_mov_b32_e32 v113, v99
	v_mov_b32_e32 v112, v98
	v_cvt_pk_bf16_f32 v98, v108, v109
	v_cvt_pk_bf16_f32 v99, v110, v111
	v_cvt_pk_bf16_f32 v100, v112, v113
	v_cvt_pk_bf16_f32 v101, v114, v115
	global_store_dwordx4 v[106:107], v[98:101], off offset:256
	s_andn2_b64 vcc, exec, s[54:55]
	s_nop 0
	v_pk_mul_f32 v[98:99], v[96:97], v[96:97]
	v_pk_mul_f32 v[100:101], v[94:95], v[94:95]
	s_nop 0
	v_pk_mov_b32 v[102:103], v[100:101], v[98:99] op_sel:[1,0]
	v_mov_b32_e32 v101, v99
	v_pk_add_f32 v[98:99], v[102:103], v[100:101]
	v_pk_mul_f32 v[100:101], v[92:93], v[92:93]
	v_pk_mul_f32 v[102:103], v[90:91], v[90:91]
	v_mov_b32_e32 v104, v100
	v_mov_b32_e32 v105, v102
	v_mov_b32_e32 v102, v101
	v_pk_add_f32 v[100:101], v[104:105], v[102:103]
	v_add_f32_e32 v98, v98, v99
	v_add_f32_e32 v98, v98, v101
	v_add_f32_e32 v98, v100, v98
	v_and_b32_e32 v100, 64, v160
	v_xor_b32_e32 v99, 16, v160
	v_add_u32_e32 v100, 64, v100
	v_cmp_lt_i32_e32 vcc, v99, v100
	s_nop 1
	v_cndmask_b32_e32 v99, v160, v99, vcc
	v_lshlrev_b32_e32 v99, 2, v99
	ds_bpermute_b32 v99, v99, v98
	s_waitcnt lgkmcnt(0)
	v_add_f32_e32 v98, v98, v99
	v_xor_b32_e32 v99, 32, v160
	v_cmp_lt_i32_e32 vcc, v99, v100
	s_nop 1
	v_cndmask_b32_e32 v99, v160, v99, vcc
	v_lshlrev_b32_e32 v99, 2, v99
	ds_bpermute_b32 v99, v99, v98
	s_waitcnt lgkmcnt(0)
	v_add_f32_e32 v98, v98, v99
	v_max_f32_e32 v99, v116, v116
	v_max_f32_e32 v106, v99, v98
	v_mov_b32_e32 v101, v97
	v_mov_b32_e32 v100, v96
	v_mov_b32_e32 v99, v95
	v_mov_b32_e32 v98, v94
	v_mov_b32_e32 v105, v93
	v_mov_b32_e32 v104, v92
	v_mov_b32_e32 v103, v91
	v_mov_b32_e32 v102, v90
	v_or_b32_e32 v90, 32, v161
	v_mad_i64_i32 v[90:91], s[72:73], s70, v90, 0
	v_lshl_add_u64 v[90:91], v[90:91], 1, v[122:123]
	v_cvt_pk_bf16_f32 v92, v98, v99
	v_cvt_pk_bf16_f32 v93, v100, v101
	v_cvt_pk_bf16_f32 v94, v102, v103
	v_cvt_pk_bf16_f32 v95, v104, v105
	global_store_dwordx4 v[90:91], v[92:95], off
	s_andn2_b64 vcc, exec, s[54:55]
	s_nop 0
	v_pk_mul_f32 v[92:93], v[88:89], v[88:89]
	v_pk_mul_f32 v[94:95], v[86:87], v[86:87]
	s_nop 0
	v_pk_mov_b32 v[96:97], v[94:95], v[92:93] op_sel:[1,0]
	v_mov_b32_e32 v95, v93
	v_pk_add_f32 v[92:93], v[96:97], v[94:95]
	v_pk_mul_f32 v[94:95], v[84:85], v[84:85]
	v_pk_mul_f32 v[96:97], v[82:83], v[82:83]
	v_mov_b32_e32 v98, v94
	v_mov_b32_e32 v99, v96
	v_mov_b32_e32 v96, v95
	v_pk_add_f32 v[94:95], v[98:99], v[96:97]
	v_add_f32_e32 v92, v92, v93
	v_add_f32_e32 v92, v92, v95
	v_add_f32_e32 v92, v94, v92
	v_and_b32_e32 v94, 64, v160
	v_xor_b32_e32 v93, 16, v160
	v_add_u32_e32 v94, 64, v94
	v_cmp_lt_i32_e32 vcc, v93, v94
	s_nop 1
	v_cndmask_b32_e32 v93, v160, v93, vcc
	v_lshlrev_b32_e32 v93, 2, v93
	ds_bpermute_b32 v93, v93, v92
	s_waitcnt lgkmcnt(0)
	v_add_f32_e32 v92, v92, v93
	v_xor_b32_e32 v93, 32, v160
	v_cmp_lt_i32_e32 vcc, v93, v94
	s_nop 1
	v_cndmask_b32_e32 v93, v160, v93, vcc
	v_lshlrev_b32_e32 v93, 2, v93
	ds_bpermute_b32 v93, v93, v92
	s_waitcnt lgkmcnt(0)
	v_add_f32_e32 v92, v92, v93
	v_max_f32_e32 v93, v106, v106
	v_max_f32_e32 v100, v93, v92
	v_mov_b32_e32 v95, v89
	v_mov_b32_e32 v94, v88
	v_mov_b32_e32 v93, v87
	v_mov_b32_e32 v92, v86
	v_mov_b32_e32 v99, v85
	v_mov_b32_e32 v98, v84
	v_mov_b32_e32 v97, v83
	v_mov_b32_e32 v96, v82
	v_cvt_pk_bf16_f32 v82, v92, v93
	v_cvt_pk_bf16_f32 v83, v94, v95
	v_cvt_pk_bf16_f32 v84, v96, v97
	v_cvt_pk_bf16_f32 v85, v98, v99
	global_store_dwordx4 v[90:91], v[82:85], off offset:256
	s_andn2_b64 vcc, exec, s[54:55]
	s_nop 0
	v_pk_mul_f32 v[82:83], v[80:81], v[80:81]
	v_pk_mul_f32 v[84:85], v[78:79], v[78:79]
	s_nop 0
	v_pk_mov_b32 v[86:87], v[84:85], v[82:83] op_sel:[1,0]
	v_mov_b32_e32 v85, v83
	v_pk_add_f32 v[82:83], v[86:87], v[84:85]
	v_pk_mul_f32 v[84:85], v[76:77], v[76:77]
	v_pk_mul_f32 v[86:87], v[74:75], v[74:75]
	v_mov_b32_e32 v88, v84
	v_mov_b32_e32 v89, v86
	v_mov_b32_e32 v86, v85
	v_pk_add_f32 v[84:85], v[88:89], v[86:87]
	v_add_f32_e32 v82, v82, v83
	v_add_f32_e32 v82, v82, v85
	v_add_f32_e32 v82, v84, v82
	v_and_b32_e32 v84, 64, v160
	v_xor_b32_e32 v83, 16, v160
	v_add_u32_e32 v84, 64, v84
	v_cmp_lt_i32_e32 vcc, v83, v84
	s_nop 1
	v_cndmask_b32_e32 v83, v160, v83, vcc
	v_lshlrev_b32_e32 v83, 2, v83
	ds_bpermute_b32 v83, v83, v82
	s_waitcnt lgkmcnt(0)
	v_add_f32_e32 v82, v82, v83
	v_xor_b32_e32 v83, 32, v160
	v_cmp_lt_i32_e32 vcc, v83, v84
	s_nop 1
	v_cndmask_b32_e32 v83, v160, v83, vcc
	v_lshlrev_b32_e32 v83, 2, v83
	ds_bpermute_b32 v83, v83, v82
	s_waitcnt lgkmcnt(0)
	v_add_f32_e32 v82, v82, v83
	v_max_f32_e32 v83, v100, v100
	v_max_f32_e32 v90, v83, v82
	v_mov_b32_e32 v85, v81
	v_mov_b32_e32 v84, v80
	v_mov_b32_e32 v83, v79
	v_mov_b32_e32 v82, v78
	v_mov_b32_e32 v89, v77
	v_mov_b32_e32 v88, v76
	v_mov_b32_e32 v87, v75
	v_mov_b32_e32 v86, v74
	v_or_b32_e32 v74, 48, v161
	v_mad_i64_i32 v[74:75], s[72:73], s70, v74, 0
	v_lshl_add_u64 v[74:75], v[74:75], 1, v[122:123]
	v_cvt_pk_bf16_f32 v76, v82, v83
	v_cvt_pk_bf16_f32 v77, v84, v85
	v_cvt_pk_bf16_f32 v78, v86, v87
	v_cvt_pk_bf16_f32 v79, v88, v89
	global_store_dwordx4 v[74:75], v[76:79], off
	s_andn2_b64 vcc, exec, s[54:55]
	s_nop 0
	v_pk_mul_f32 v[76:77], v[72:73], v[72:73]
	v_pk_mul_f32 v[78:79], v[70:71], v[70:71]
	s_nop 0
	v_pk_mov_b32 v[80:81], v[78:79], v[76:77] op_sel:[1,0]
	v_mov_b32_e32 v79, v77
	v_pk_add_f32 v[76:77], v[80:81], v[78:79]
	v_pk_mul_f32 v[78:79], v[68:69], v[68:69]
	v_pk_mul_f32 v[80:81], v[66:67], v[66:67]
	v_mov_b32_e32 v82, v78
	v_mov_b32_e32 v83, v80
	v_mov_b32_e32 v80, v79
	v_pk_add_f32 v[78:79], v[82:83], v[80:81]
	v_add_f32_e32 v76, v76, v77
	v_add_f32_e32 v76, v76, v79
	v_add_f32_e32 v76, v78, v76
	v_and_b32_e32 v78, 64, v160
	v_xor_b32_e32 v77, 16, v160
	v_add_u32_e32 v78, 64, v78
	v_cmp_lt_i32_e32 vcc, v77, v78
	s_nop 1
	v_cndmask_b32_e32 v77, v160, v77, vcc
	v_lshlrev_b32_e32 v77, 2, v77
	ds_bpermute_b32 v77, v77, v76
	s_waitcnt lgkmcnt(0)
	v_add_f32_e32 v76, v76, v77
	v_xor_b32_e32 v77, 32, v160
	v_cmp_lt_i32_e32 vcc, v77, v78
	s_nop 1
	v_cndmask_b32_e32 v77, v160, v77, vcc
	v_lshlrev_b32_e32 v77, 2, v77
	ds_bpermute_b32 v77, v77, v76
	s_waitcnt lgkmcnt(0)
	v_add_f32_e32 v76, v76, v77
	v_max_f32_e32 v77, v90, v90
	v_max_f32_e32 v84, v77, v76
	v_mov_b32_e32 v79, v73
	v_mov_b32_e32 v78, v72
	v_mov_b32_e32 v77, v71
	v_mov_b32_e32 v76, v70
	v_mov_b32_e32 v83, v69
	v_mov_b32_e32 v82, v68
	v_mov_b32_e32 v81, v67
	v_mov_b32_e32 v80, v66
	v_cvt_pk_bf16_f32 v66, v76, v77
	v_cvt_pk_bf16_f32 v67, v78, v79
	v_cvt_pk_bf16_f32 v68, v80, v81
	v_cvt_pk_bf16_f32 v69, v82, v83
	global_store_dwordx4 v[74:75], v[66:69], off offset:256
	s_andn2_b64 vcc, exec, s[54:55]
	s_nop 0
	v_pk_mul_f32 v[66:67], v[64:65], v[64:65]
	v_pk_mul_f32 v[68:69], v[62:63], v[62:63]
	s_nop 0
	v_pk_mov_b32 v[70:71], v[68:69], v[66:67] op_sel:[1,0]
	v_mov_b32_e32 v69, v67
	v_pk_add_f32 v[66:67], v[70:71], v[68:69]
	v_pk_mul_f32 v[68:69], v[60:61], v[60:61]
	v_pk_mul_f32 v[70:71], v[58:59], v[58:59]
	v_mov_b32_e32 v72, v68
	v_mov_b32_e32 v73, v70
	v_mov_b32_e32 v70, v69
	v_pk_add_f32 v[68:69], v[72:73], v[70:71]
	v_add_f32_e32 v66, v66, v67
	v_add_f32_e32 v66, v66, v69
	v_add_f32_e32 v66, v68, v66
	v_and_b32_e32 v68, 64, v160
	v_xor_b32_e32 v67, 16, v160
	v_add_u32_e32 v68, 64, v68
	v_cmp_lt_i32_e32 vcc, v67, v68
	s_nop 1
	v_cndmask_b32_e32 v67, v160, v67, vcc
	v_lshlrev_b32_e32 v67, 2, v67
	ds_bpermute_b32 v67, v67, v66
	s_waitcnt lgkmcnt(0)
	v_add_f32_e32 v66, v66, v67
	v_xor_b32_e32 v67, 32, v160
	v_cmp_lt_i32_e32 vcc, v67, v68
	s_nop 1
	v_cndmask_b32_e32 v67, v160, v67, vcc
	v_lshlrev_b32_e32 v67, 2, v67
	ds_bpermute_b32 v67, v67, v66
	s_waitcnt lgkmcnt(0)
	v_add_f32_e32 v66, v66, v67
	v_max_f32_e32 v67, v84, v84
	v_max_f32_e32 v74, v67, v66
	v_mov_b32_e32 v69, v65
	v_mov_b32_e32 v68, v64
	v_mov_b32_e32 v67, v63
	v_mov_b32_e32 v66, v62
	v_mov_b32_e32 v73, v61
	v_mov_b32_e32 v72, v60
	v_mov_b32_e32 v71, v59
	v_mov_b32_e32 v70, v58
	v_add_u32_e32 v58, 0x80, v161
	v_mad_i64_i32 v[58:59], s[72:73], s70, v58, 0
	v_lshl_add_u64 v[58:59], v[58:59], 1, v[122:123]
	v_cvt_pk_bf16_f32 v60, v66, v67
	v_cvt_pk_bf16_f32 v61, v68, v69
	v_cvt_pk_bf16_f32 v62, v70, v71
	v_cvt_pk_bf16_f32 v63, v72, v73
	global_store_dwordx4 v[58:59], v[60:63], off
	s_andn2_b64 vcc, exec, s[54:55]
	s_nop 0
	v_pk_mul_f32 v[60:61], v[56:57], v[56:57]
	v_pk_mul_f32 v[62:63], v[54:55], v[54:55]
	s_nop 0
	v_pk_mov_b32 v[64:65], v[62:63], v[60:61] op_sel:[1,0]
	v_mov_b32_e32 v63, v61
	v_pk_add_f32 v[60:61], v[64:65], v[62:63]
	v_pk_mul_f32 v[62:63], v[52:53], v[52:53]
	v_pk_mul_f32 v[64:65], v[50:51], v[50:51]
	v_mov_b32_e32 v66, v62
	v_mov_b32_e32 v67, v64
	v_mov_b32_e32 v64, v63
	v_pk_add_f32 v[62:63], v[66:67], v[64:65]
	v_add_f32_e32 v60, v60, v61
	v_add_f32_e32 v60, v60, v63
	v_add_f32_e32 v60, v62, v60
	v_and_b32_e32 v62, 64, v160
	v_xor_b32_e32 v61, 16, v160
	v_add_u32_e32 v62, 64, v62
	v_cmp_lt_i32_e32 vcc, v61, v62
	s_nop 1
	v_cndmask_b32_e32 v61, v160, v61, vcc
	v_lshlrev_b32_e32 v61, 2, v61
	ds_bpermute_b32 v61, v61, v60
	s_waitcnt lgkmcnt(0)
	v_add_f32_e32 v60, v60, v61
	v_xor_b32_e32 v61, 32, v160
	v_cmp_lt_i32_e32 vcc, v61, v62
	s_nop 1
	v_cndmask_b32_e32 v61, v160, v61, vcc
	v_lshlrev_b32_e32 v61, 2, v61
	ds_bpermute_b32 v61, v61, v60
	s_waitcnt lgkmcnt(0)
	v_add_f32_e32 v60, v60, v61
	v_max_f32_e32 v61, v74, v74
	v_max_f32_e32 v68, v61, v60
	v_mov_b32_e32 v63, v57
	v_mov_b32_e32 v62, v56
	v_mov_b32_e32 v61, v55
	v_mov_b32_e32 v60, v54
	v_mov_b32_e32 v67, v53
	v_mov_b32_e32 v66, v52
	v_mov_b32_e32 v65, v51
	v_mov_b32_e32 v64, v50
	v_cvt_pk_bf16_f32 v50, v60, v61
	v_cvt_pk_bf16_f32 v51, v62, v63
	v_cvt_pk_bf16_f32 v52, v64, v65
	v_cvt_pk_bf16_f32 v53, v66, v67
	global_store_dwordx4 v[58:59], v[50:53], off offset:256
	s_andn2_b64 vcc, exec, s[54:55]
	s_nop 0
	v_pk_mul_f32 v[50:51], v[48:49], v[48:49]
	v_pk_mul_f32 v[52:53], v[46:47], v[46:47]
	s_nop 0
	v_pk_mov_b32 v[54:55], v[52:53], v[50:51] op_sel:[1,0]
	v_mov_b32_e32 v53, v51
	v_pk_add_f32 v[50:51], v[54:55], v[52:53]
	v_pk_mul_f32 v[52:53], v[44:45], v[44:45]
	v_pk_mul_f32 v[54:55], v[42:43], v[42:43]
	v_mov_b32_e32 v56, v52
	v_mov_b32_e32 v57, v54
	v_mov_b32_e32 v54, v53
	v_pk_add_f32 v[52:53], v[56:57], v[54:55]
	v_add_f32_e32 v50, v50, v51
	v_add_f32_e32 v50, v50, v53
	v_add_f32_e32 v50, v52, v50
	v_and_b32_e32 v52, 64, v160
	v_xor_b32_e32 v51, 16, v160
	v_add_u32_e32 v52, 64, v52
	v_cmp_lt_i32_e32 vcc, v51, v52
	s_nop 1
	v_cndmask_b32_e32 v51, v160, v51, vcc
	v_lshlrev_b32_e32 v51, 2, v51
	ds_bpermute_b32 v51, v51, v50
	s_waitcnt lgkmcnt(0)
	v_add_f32_e32 v50, v50, v51
	v_xor_b32_e32 v51, 32, v160
	v_cmp_lt_i32_e32 vcc, v51, v52
	s_nop 1
	v_cndmask_b32_e32 v51, v160, v51, vcc
	v_lshlrev_b32_e32 v51, 2, v51
	ds_bpermute_b32 v51, v51, v50
	s_waitcnt lgkmcnt(0)
	v_add_f32_e32 v50, v50, v51
	v_max_f32_e32 v51, v68, v68
	v_max_f32_e32 v58, v51, v50
	v_mov_b32_e32 v53, v49
	v_mov_b32_e32 v52, v48
	v_mov_b32_e32 v51, v47
	v_mov_b32_e32 v50, v46
	v_mov_b32_e32 v57, v45
	v_mov_b32_e32 v56, v44
	v_mov_b32_e32 v55, v43
	v_mov_b32_e32 v54, v42
	v_add_u32_e32 v42, 0x90, v161
	v_mad_i64_i32 v[42:43], s[72:73], s70, v42, 0
	v_lshl_add_u64 v[42:43], v[42:43], 1, v[122:123]
	v_cvt_pk_bf16_f32 v44, v50, v51
	v_cvt_pk_bf16_f32 v45, v52, v53
	v_cvt_pk_bf16_f32 v46, v54, v55
	v_cvt_pk_bf16_f32 v47, v56, v57
	global_store_dwordx4 v[42:43], v[44:47], off
	s_andn2_b64 vcc, exec, s[54:55]
	s_nop 0
	v_pk_mul_f32 v[44:45], v[40:41], v[40:41]
	v_pk_mul_f32 v[46:47], v[38:39], v[38:39]
	s_nop 0
	v_pk_mov_b32 v[48:49], v[46:47], v[44:45] op_sel:[1,0]
	v_mov_b32_e32 v47, v45
	v_pk_add_f32 v[44:45], v[48:49], v[46:47]
	v_pk_mul_f32 v[46:47], v[36:37], v[36:37]
	v_pk_mul_f32 v[48:49], v[34:35], v[34:35]
	v_mov_b32_e32 v50, v46
	v_mov_b32_e32 v51, v48
	v_mov_b32_e32 v48, v47
	v_pk_add_f32 v[46:47], v[50:51], v[48:49]
	v_add_f32_e32 v44, v44, v45
	v_add_f32_e32 v44, v44, v47
	v_add_f32_e32 v44, v46, v44
	v_and_b32_e32 v46, 64, v160
	v_xor_b32_e32 v45, 16, v160
	v_add_u32_e32 v46, 64, v46
	v_cmp_lt_i32_e32 vcc, v45, v46
	s_nop 1
	v_cndmask_b32_e32 v45, v160, v45, vcc
	v_lshlrev_b32_e32 v45, 2, v45
	ds_bpermute_b32 v45, v45, v44
	s_waitcnt lgkmcnt(0)
	v_add_f32_e32 v44, v44, v45
	v_xor_b32_e32 v45, 32, v160
	v_cmp_lt_i32_e32 vcc, v45, v46
	s_nop 1
	v_cndmask_b32_e32 v45, v160, v45, vcc
	v_lshlrev_b32_e32 v45, 2, v45
	ds_bpermute_b32 v45, v45, v44
	s_waitcnt lgkmcnt(0)
	v_add_f32_e32 v44, v44, v45
	v_max_f32_e32 v45, v58, v58
	v_max_f32_e32 v52, v45, v44
	v_mov_b32_e32 v47, v41
	v_mov_b32_e32 v46, v40
	v_mov_b32_e32 v45, v39
	v_mov_b32_e32 v44, v38
	v_mov_b32_e32 v51, v37
	v_mov_b32_e32 v50, v36
	v_mov_b32_e32 v49, v35
	v_mov_b32_e32 v48, v34
	v_cvt_pk_bf16_f32 v34, v44, v45
	v_cvt_pk_bf16_f32 v35, v46, v47
	v_cvt_pk_bf16_f32 v36, v48, v49
	v_cvt_pk_bf16_f32 v37, v50, v51
	global_store_dwordx4 v[42:43], v[34:37], off offset:256
	s_andn2_b64 vcc, exec, s[54:55]
	s_nop 0
	v_pk_mul_f32 v[34:35], v[32:33], v[32:33]
	v_pk_mul_f32 v[36:37], v[30:31], v[30:31]
	s_nop 0
	v_pk_mov_b32 v[38:39], v[36:37], v[34:35] op_sel:[1,0]
	v_mov_b32_e32 v37, v35
	v_pk_add_f32 v[34:35], v[38:39], v[36:37]
	v_pk_mul_f32 v[36:37], v[28:29], v[28:29]
	v_pk_mul_f32 v[38:39], v[26:27], v[26:27]
	v_mov_b32_e32 v40, v36
	v_mov_b32_e32 v41, v38
	v_mov_b32_e32 v38, v37
	v_pk_add_f32 v[36:37], v[40:41], v[38:39]
	v_add_f32_e32 v34, v34, v35
	v_add_f32_e32 v34, v34, v37
	v_add_f32_e32 v34, v36, v34
	v_and_b32_e32 v36, 64, v160
	v_xor_b32_e32 v35, 16, v160
	v_add_u32_e32 v36, 64, v36
	v_cmp_lt_i32_e32 vcc, v35, v36
	s_nop 1
	v_cndmask_b32_e32 v35, v160, v35, vcc
	v_lshlrev_b32_e32 v35, 2, v35
	ds_bpermute_b32 v35, v35, v34
	s_waitcnt lgkmcnt(0)
	v_add_f32_e32 v34, v34, v35
	v_xor_b32_e32 v35, 32, v160
	v_cmp_lt_i32_e32 vcc, v35, v36
	s_nop 1
	v_cndmask_b32_e32 v35, v160, v35, vcc
	v_lshlrev_b32_e32 v35, 2, v35
	ds_bpermute_b32 v35, v35, v34
	s_waitcnt lgkmcnt(0)
	v_add_f32_e32 v34, v34, v35
	v_max_f32_e32 v35, v52, v52
	v_max_f32_e32 v42, v35, v34
	v_mov_b32_e32 v37, v33
	v_mov_b32_e32 v36, v32
	v_mov_b32_e32 v35, v31
	v_mov_b32_e32 v34, v30
	v_mov_b32_e32 v41, v29
	v_mov_b32_e32 v40, v28
	v_mov_b32_e32 v39, v27
	v_mov_b32_e32 v38, v26
	v_add_u32_e32 v26, 0xa0, v161
	v_mad_i64_i32 v[26:27], s[72:73], s70, v26, 0
	v_lshl_add_u64 v[26:27], v[26:27], 1, v[122:123]
	v_cvt_pk_bf16_f32 v28, v34, v35
	v_cvt_pk_bf16_f32 v29, v36, v37
	v_cvt_pk_bf16_f32 v30, v38, v39
	v_cvt_pk_bf16_f32 v31, v40, v41
	global_store_dwordx4 v[26:27], v[28:31], off
	s_andn2_b64 vcc, exec, s[54:55]
	s_nop 0
	v_pk_mul_f32 v[28:29], v[24:25], v[24:25]
	v_pk_mul_f32 v[30:31], v[22:23], v[22:23]
	s_nop 0
	v_pk_mov_b32 v[32:33], v[30:31], v[28:29] op_sel:[1,0]
	v_mov_b32_e32 v31, v29
	v_pk_add_f32 v[28:29], v[32:33], v[30:31]
	v_pk_mul_f32 v[30:31], v[20:21], v[20:21]
	v_pk_mul_f32 v[32:33], v[18:19], v[18:19]
	v_mov_b32_e32 v34, v30
	v_mov_b32_e32 v35, v32
	v_mov_b32_e32 v32, v31
	v_pk_add_f32 v[30:31], v[34:35], v[32:33]
	v_add_f32_e32 v28, v28, v29
	v_add_f32_e32 v28, v28, v31
	v_add_f32_e32 v28, v30, v28
	v_and_b32_e32 v30, 64, v160
	v_xor_b32_e32 v29, 16, v160
	v_add_u32_e32 v30, 64, v30
	v_cmp_lt_i32_e32 vcc, v29, v30
	s_nop 1
	v_cndmask_b32_e32 v29, v160, v29, vcc
	v_lshlrev_b32_e32 v29, 2, v29
	ds_bpermute_b32 v29, v29, v28
	s_waitcnt lgkmcnt(0)
	v_add_f32_e32 v28, v28, v29
	v_xor_b32_e32 v29, 32, v160
	v_cmp_lt_i32_e32 vcc, v29, v30
	s_nop 1
	v_cndmask_b32_e32 v29, v160, v29, vcc
	v_lshlrev_b32_e32 v29, 2, v29
	ds_bpermute_b32 v29, v29, v28
	s_waitcnt lgkmcnt(0)
	v_add_f32_e32 v28, v28, v29
	v_max_f32_e32 v29, v42, v42
	v_max_f32_e32 v36, v29, v28
	v_mov_b32_e32 v31, v25
	v_mov_b32_e32 v30, v24
	v_mov_b32_e32 v29, v23
	v_mov_b32_e32 v28, v22
	v_mov_b32_e32 v35, v21
	v_mov_b32_e32 v34, v20
	v_mov_b32_e32 v33, v19
	v_mov_b32_e32 v32, v18
	v_cvt_pk_bf16_f32 v18, v28, v29
	v_cvt_pk_bf16_f32 v19, v30, v31
	v_cvt_pk_bf16_f32 v20, v32, v33
	v_cvt_pk_bf16_f32 v21, v34, v35
	global_store_dwordx4 v[26:27], v[18:21], off offset:256
	s_andn2_b64 vcc, exec, s[54:55]
	s_nop 0
	v_pk_mul_f32 v[18:19], v[16:17], v[16:17]
	v_pk_mul_f32 v[20:21], v[14:15], v[14:15]
	s_nop 0
	v_pk_mov_b32 v[22:23], v[20:21], v[18:19] op_sel:[1,0]
	v_mov_b32_e32 v21, v19
	v_pk_add_f32 v[18:19], v[22:23], v[20:21]
	v_pk_mul_f32 v[20:21], v[12:13], v[12:13]
	v_pk_mul_f32 v[22:23], v[10:11], v[10:11]
	v_mov_b32_e32 v24, v20
	v_mov_b32_e32 v25, v22
	v_mov_b32_e32 v22, v21
	v_pk_add_f32 v[20:21], v[24:25], v[22:23]
	v_add_f32_e32 v18, v18, v19
	v_add_f32_e32 v18, v18, v21
	v_add_f32_e32 v18, v20, v18
	v_and_b32_e32 v20, 64, v160
	v_xor_b32_e32 v19, 16, v160
	v_add_u32_e32 v20, 64, v20
	v_cmp_lt_i32_e32 vcc, v19, v20
	s_nop 1
	v_cndmask_b32_e32 v19, v160, v19, vcc
	v_lshlrev_b32_e32 v19, 2, v19
	ds_bpermute_b32 v19, v19, v18
	s_waitcnt lgkmcnt(0)
	v_add_f32_e32 v18, v18, v19
	v_xor_b32_e32 v19, 32, v160
	v_cmp_lt_i32_e32 vcc, v19, v20
	s_nop 1
	v_cndmask_b32_e32 v19, v160, v19, vcc
	v_lshlrev_b32_e32 v19, 2, v19
	ds_bpermute_b32 v19, v19, v18
	s_waitcnt lgkmcnt(0)
	v_add_f32_e32 v18, v18, v19
	v_max_f32_e32 v19, v36, v36
	v_max_f32_e32 v26, v19, v18
	v_mov_b32_e32 v21, v17
	v_mov_b32_e32 v20, v16
	v_mov_b32_e32 v19, v15
	v_mov_b32_e32 v18, v14
	v_mov_b32_e32 v25, v13
	v_mov_b32_e32 v24, v12
	v_mov_b32_e32 v23, v11
	v_mov_b32_e32 v22, v10
	s_mov_b64 s[72:73], 0
	v_add_u32_e32 v10, 0xb0, v161
	v_mad_i64_i32 v[10:11], s[70:71], s70, v10, 0
	v_lshl_add_u64 v[10:11], v[10:11], 1, v[122:123]
	v_cvt_pk_bf16_f32 v12, v18, v19
	v_cvt_pk_bf16_f32 v13, v20, v21
	v_cvt_pk_bf16_f32 v14, v22, v23
	v_cvt_pk_bf16_f32 v15, v24, v25
	global_store_dwordx4 v[10:11], v[12:15], off
	s_andn2_b64 vcc, exec, s[54:55]
	s_nop 0
	v_pk_mul_f32 v[12:13], v[8:9], v[8:9]
	v_pk_mul_f32 v[14:15], v[6:7], v[6:7]
	s_nop 0
	v_pk_mov_b32 v[16:17], v[14:15], v[12:13] op_sel:[1,0]
	v_mov_b32_e32 v15, v13
	v_pk_add_f32 v[12:13], v[16:17], v[14:15]
	v_pk_mul_f32 v[14:15], v[4:5], v[4:5]
	v_pk_mul_f32 v[16:17], v[2:3], v[2:3]
	v_mov_b32_e32 v18, v14
	v_mov_b32_e32 v19, v16
	v_mov_b32_e32 v16, v15
	v_pk_add_f32 v[14:15], v[18:19], v[16:17]
	v_add_f32_e32 v12, v12, v13
	v_add_f32_e32 v12, v12, v15
	v_add_f32_e32 v12, v14, v12
	v_and_b32_e32 v14, 64, v160
	v_xor_b32_e32 v13, 16, v160
	v_add_u32_e32 v14, 64, v14
	v_cmp_lt_i32_e32 vcc, v13, v14
	s_nop 1
	v_cndmask_b32_e32 v13, v160, v13, vcc
	v_lshlrev_b32_e32 v13, 2, v13
	ds_bpermute_b32 v13, v13, v12
	s_waitcnt lgkmcnt(0)
	v_add_f32_e32 v12, v12, v13
	v_xor_b32_e32 v13, 32, v160
	v_cmp_lt_i32_e32 vcc, v13, v14
	s_nop 1
	v_cndmask_b32_e32 v13, v160, v13, vcc
	v_lshlrev_b32_e32 v13, 2, v13
	ds_bpermute_b32 v13, v13, v12
	s_waitcnt lgkmcnt(0)
	v_add_f32_e32 v12, v12, v13
	v_max_f32_e32 v13, v26, v26
	v_max_f32_e32 v20, v13, v12
	v_mov_b32_e32 v15, v9
	v_mov_b32_e32 v14, v8
	v_mov_b32_e32 v13, v7
	v_mov_b32_e32 v12, v6
	v_mov_b32_e32 v19, v5
	v_mov_b32_e32 v18, v4
	v_mov_b32_e32 v17, v3
	v_mov_b32_e32 v16, v2
	s_mov_b64 s[6:7], 0
	s_mov_b64 s[8:9], 0
	s_and_b64 vcc, exec, s[54:55]
	v_cvt_pk_bf16_f32 v2, v12, v13
	v_cvt_pk_bf16_f32 v3, v14, v15
	v_cvt_pk_bf16_f32 v4, v16, v17
	v_cvt_pk_bf16_f32 v5, v18, v19
	global_store_dwordx4 v[10:11], v[2:5], off offset:256
	s_branch .Lmy_e1_act4_tail
	s_xor_b64 s[74:75], s[74:75], -1
	s_mov_b64 s[78:79], -1
	s_xor_b64 s[76:77], s[76:77], -1
	s_and_b64 vcc, exec, s[74:75]
	s_cbranch_vccz .LBB0_197
	s_and_b64 vcc, exec, s[76:77]
	s_cbranch_vccz .LBB0_194
	s_and_b64 vcc, exec, s[56:57]
	s_cbranch_vccz .LBB0_191
	s_andn2_b64 vcc, exec, s[54:55]
	v_mov_b32_e32 v162, 0
	s_cbranch_vccnz .LBB0_190
	v_pk_mul_f32 v[146:147], v[128:129], v[128:129]
	v_pk_mul_f32 v[148:149], v[126:127], v[126:127]
	s_nop 0
	v_pk_mov_b32 v[150:151], v[148:149], v[146:147] op_sel:[1,0]
	v_mov_b32_e32 v149, v147
	v_pk_add_f32 v[146:147], v[150:151], v[148:149]
	v_pk_mul_f32 v[148:149], v[124:125], v[124:125]
	v_pk_mul_f32 v[150:151], v[122:123], v[122:123]
	v_mov_b32_e32 v152, v148
	v_mov_b32_e32 v153, v150
	v_mov_b32_e32 v150, v149
	v_pk_add_f32 v[148:149], v[152:153], v[150:151]
	v_add_f32_e32 v146, v146, v147
	v_add_f32_e32 v146, v146, v149
	v_add_f32_e32 v146, v148, v146
	v_and_b32_e32 v148, 64, v160
	v_xor_b32_e32 v147, 16, v160
	v_add_u32_e32 v148, 64, v148
	v_cmp_lt_i32_e32 vcc, v147, v148
	s_nop 1
	v_cndmask_b32_e32 v147, v160, v147, vcc
	v_lshlrev_b32_e32 v147, 2, v147
	ds_bpermute_b32 v147, v147, v146
	s_waitcnt lgkmcnt(0)
	v_add_f32_e32 v146, v146, v147
	v_xor_b32_e32 v147, 32, v160
	v_cmp_lt_i32_e32 vcc, v147, v148
	s_nop 1
	v_cndmask_b32_e32 v147, v160, v147, vcc
	v_lshlrev_b32_e32 v147, 2, v147
	ds_bpermute_b32 v147, v147, v146
	s_waitcnt lgkmcnt(0)
	v_add_f32_e32 v146, v146, v147
	v_max_f32_e32 v162, 0, v146

.Lmy_e1_act4_tail:
	s_nop 0
	v_and_b32_e32 v2, 64, v160
	v_add_u32_e32 v3, 64, v2
	v_xor_b32_e32 v2, 1, v160
	v_cmp_lt_i32_e32 vcc, v2, v3
	v_xor_b32_e32 v5, 2, v160
	v_max_f32_e32 v4, v20, v20
	v_cndmask_b32_e32 v2, v160, v2, vcc
	v_lshlrev_b32_e32 v2, 2, v2
	ds_bpermute_b32 v2, v2, v20
	v_cmp_lt_i32_e32 vcc, v5, v3
	s_waitcnt lgkmcnt(0)
	v_max_f32_e32 v2, v2, v2
	v_max_f32_e32 v2, v4, v2
	v_cndmask_b32_e32 v4, v160, v5, vcc
	v_lshlrev_b32_e32 v4, 2, v4
	ds_bpermute_b32 v4, v4, v2
	v_xor_b32_e32 v5, 4, v160
	v_cmp_lt_i32_e32 vcc, v5, v3
	s_waitcnt lgkmcnt(0)
	v_max_f32_e32 v4, v4, v4
	v_max_f32_e32 v2, v2, v4
	v_cndmask_b32_e32 v4, v160, v5, vcc
	v_lshlrev_b32_e32 v4, 2, v4
	ds_bpermute_b32 v4, v4, v2
	v_xor_b32_e32 v5, 8, v160
	v_cmp_lt_i32_e32 vcc, v5, v3
	s_waitcnt lgkmcnt(0)
	v_max_f32_e32 v4, v4, v4
	v_cndmask_b32_e32 v3, v160, v5, vcc
	v_max_f32_e32 v2, v2, v4
	v_lshlrev_b32_e32 v3, 2, v3
	ds_bpermute_b32 v3, v3, v2
	s_and_saveexec_b64 s[6:7], s[0:1]
	s_cbranch_execz .LBB0_415
	s_waitcnt lgkmcnt(0)
	v_max_f32_e32 v3, v3, v3
	v_max_f32_e32 v2, v2, v2
	s_mov_b64 s[8:9], exec
	v_max_f32_e32 v2, v2, v3
	s_mov_b32 s23, 0
